# HGRN passC state walk: batch the 40 loads of a step behind one wait
# speedup vs baseline: 1.0040x; 1.0040x over previous
; DI void hgrn_passC(const Params& P, LAS unsigned char* lds, int u) {
;     ...
;           const int uj = (u - sc) + jj; const float* SE = SEb + (size_t)uj * 16384; const float* DT = DTb + uj * 128;
;           float wmax = 0.f;
; #pragma unroll
;           for (int dt = 0; dt < 8; ++dt) {
;               const f32x4 dv = *(const f32x4*)(DT + 16 * dt + 4 * g);
; #pragma unroll
;               for (int j = 0; j < 4; ++j) acc[dt][j] += W[dt][j] * SE[(16 * dt + 4 * g + j) * 128 + 16 * w + r16];
;               W[dt] *= dv; wmax = fmaxf(wmax, fmaxf(fmaxf(W[dt][0], W[dt][1]), fmaxf(W[dt][2], W[dt][3]))); }
;           if (!__any(wmax > 0.f)) break;
.LBB0_88:
	s_cmp_lt_i32 s7, 1
	s_cbranch_scc1 .LBB0_87
	s_add_i32 s12, s36, s7
	s_ashr_i32 s13, s12, 31
	s_add_i32 s39, s7, -1
	s_lshl_b64 s[12:13], s[12:13], 16
	s_add_u32 s34, s98, s12
	s_addc_u32 s35, s99, s13
	s_ashr_i32 s7, s6, 31
	v_lshl_add_u64 v[36:37], s[6:7], 2, v[40:41]
	v_lshlrev_b32_e32 v218, 2, v42
	v_add_u32_e32 v219, 0x2000, v218
	v_add_u32_e32 v220, 0x4000, v218
	v_add_u32_e32 v221, 0x6000, v218
	v_add_u32_e32 v222, 0x8000, v218
	v_add_u32_e32 v223, 0xa000, v218
	v_add_u32_e32 v224, 0xc000, v218
	v_add_u32_e32 v225, 0xe000, v218
	global_load_dwordx4 v[184:187], v[36:37], off
	global_load_dwordx4 v[188:191], v[36:37], off offset:64
	global_load_dwordx4 v[192:195], v[36:37], off offset:128
	global_load_dwordx4 v[196:199], v[36:37], off offset:192
	global_load_dwordx4 v[200:203], v[36:37], off offset:256
	global_load_dwordx4 v[204:207], v[36:37], off offset:320
	global_load_dwordx4 v[208:211], v[36:37], off offset:384
	global_load_dwordx4 v[212:215], v[36:37], off offset:448
	global_load_dword v152, v218, s[34:35]
	global_load_dword v153, v218, s[34:35] offset:512
	global_load_dword v154, v218, s[34:35] offset:1024
	global_load_dword v155, v218, s[34:35] offset:1536
	global_load_dword v156, v219, s[34:35]
	global_load_dword v157, v219, s[34:35] offset:512
	global_load_dword v158, v219, s[34:35] offset:1024
	global_load_dword v159, v219, s[34:35] offset:1536
	global_load_dword v160, v220, s[34:35]
	global_load_dword v161, v220, s[34:35] offset:512
	global_load_dword v162, v220, s[34:35] offset:1024
	global_load_dword v163, v220, s[34:35] offset:1536
	global_load_dword v164, v221, s[34:35]
	global_load_dword v165, v221, s[34:35] offset:512
	global_load_dword v166, v221, s[34:35] offset:1024
	global_load_dword v167, v221, s[34:35] offset:1536
	global_load_dword v168, v222, s[34:35]
	global_load_dword v169, v222, s[34:35] offset:512
	global_load_dword v170, v222, s[34:35] offset:1024
	global_load_dword v171, v222, s[34:35] offset:1536
	global_load_dword v172, v223, s[34:35]
	global_load_dword v173, v223, s[34:35] offset:512
	global_load_dword v174, v223, s[34:35] offset:1024
	global_load_dword v175, v223, s[34:35] offset:1536
	global_load_dword v176, v224, s[34:35]
	global_load_dword v177, v224, s[34:35] offset:512
	global_load_dword v178, v224, s[34:35] offset:1024
	global_load_dword v179, v224, s[34:35] offset:1536
	global_load_dword v180, v225, s[34:35]
	global_load_dword v181, v225, s[34:35] offset:512
	global_load_dword v182, v225, s[34:35] offset:1024
	global_load_dword v183, v225, s[34:35] offset:1536
	s_mov_b32 s7, s39
	s_waitcnt vmcnt(0)
	v_pk_fma_f32 v[32:33], v[134:135], v[152:153], v[32:33]
	v_pk_fma_f32 v[34:35], v[136:137], v[154:155], v[34:35]
	v_pk_mul_f32 v[136:137], v[136:137], v[186:187]
	v_pk_mul_f32 v[134:135], v[134:135], v[184:185]
	v_pk_fma_f32 v[28:29], v[130:131], v[156:157], v[28:29]
	v_pk_fma_f32 v[30:31], v[132:133], v[158:159], v[30:31]
	v_pk_mul_f32 v[132:133], v[132:133], v[190:191]
	v_pk_mul_f32 v[130:131], v[130:131], v[188:189]
	v_pk_fma_f32 v[24:25], v[126:127], v[160:161], v[24:25]
	v_pk_fma_f32 v[26:27], v[128:129], v[162:163], v[26:27]
	v_pk_mul_f32 v[128:129], v[128:129], v[194:195]
	v_pk_mul_f32 v[126:127], v[126:127], v[192:193]
	v_pk_fma_f32 v[20:21], v[122:123], v[164:165], v[20:21]
	v_pk_fma_f32 v[22:23], v[124:125], v[166:167], v[22:23]
	v_pk_mul_f32 v[124:125], v[124:125], v[198:199]
	v_pk_mul_f32 v[122:123], v[122:123], v[196:197]
	v_pk_fma_f32 v[16:17], v[118:119], v[168:169], v[16:17]
	v_pk_fma_f32 v[18:19], v[120:121], v[170:171], v[18:19]
	v_pk_mul_f32 v[120:121], v[120:121], v[202:203]
	v_pk_mul_f32 v[118:119], v[118:119], v[200:201]
	v_pk_fma_f32 v[12:13], v[114:115], v[172:173], v[12:13]
	v_pk_fma_f32 v[14:15], v[116:117], v[174:175], v[14:15]
	v_pk_mul_f32 v[116:117], v[116:117], v[206:207]
	v_pk_mul_f32 v[114:115], v[114:115], v[204:205]
	v_pk_fma_f32 v[8:9], v[110:111], v[176:177], v[8:9]
	v_pk_fma_f32 v[10:11], v[112:113], v[178:179], v[10:11]
	v_pk_mul_f32 v[112:113], v[112:113], v[210:211]
	v_pk_mul_f32 v[110:111], v[110:111], v[208:209]
	v_pk_fma_f32 v[4:5], v[108:109], v[180:181], v[4:5]
	v_pk_fma_f32 v[6:7], v[2:3], v[182:183], v[6:7]
	v_pk_mul_f32 v[2:3], v[2:3], v[214:215]
	v_pk_mul_f32 v[108:109], v[108:109], v[212:213]
	v_max_f32_e32 v0, v136, v137
	v_max3_f32 v0, v134, v135, v0
	v_max3_f32 v0, v0, v132, v133
	v_max3_f32 v0, v0, v130, v131
	v_max3_f32 v0, v0, v128, v129
	v_max3_f32 v0, v0, v126, v127
	v_max3_f32 v0, v0, v124, v125
	v_max3_f32 v0, v0, v122, v123
	v_max3_f32 v0, v0, v120, v121
	v_max3_f32 v0, v0, v118, v119
	v_max3_f32 v0, v0, v116, v117
	v_max3_f32 v0, v0, v114, v115
	v_max3_f32 v0, v0, v112, v113
	v_max3_f32 v0, v0, v110, v111
	v_max3_f32 v0, v0, v2, v3
	v_max3_f32 v0, v0, v108, v109
	v_max_f32_e32 v0, 0, v0
	v_cmp_lt_f32_e32 vcc, 0, v0
	s_cmp_eq_u64 vcc, 0
	s_cselect_b64 s[34:35], -1, 0
	s_addk_i32 s6, 0xff80
	s_andn2_b64 vcc, exec, s[34:35]
	s_cbranch_vccnz .LBB0_88

; DI unsigned cvt_pk_bf16(float lo, float hi) { unsigned r; asm volatile("v_cvt_pk_bf16_f32 %0, %1, %2" : "=v"(r) : "v"(lo), "v"(hi)); return r; }
;     DI void operator()(const f32x4 (&acc)[2][2][4][2], const Unit& u, int wr, int wc, int fr, int fq) const {
;     ...
;                 const int rloc = wr * 64 + fr, col0 = colb + wc * 32 + 8 * fq;
; #pragma unroll
;                 for (int ai = 0; ai < 2; ++ai)
; #pragma unroll
;                     for (int m = 0; m < 4; ++m) { bf16_t* rowp = base + (size_t)(rowb + rloc + ai * HALF + m * 16) * ld + col0;
;                         const float rs_ = ss_in ? rsqrtf(ss_in[row0 + ai * HALF + m * 16] * (1.f / DM) + EPS) : 1.f;
; #pragma unroll
;                         for (int bj = 0; bj < 2; ++bj) { const f32x4 v0 = acc[ai][bj][m][0] * rs_, v1 = acc[ai][bj][m][1] * rs_;
;                             u32x4 w; w.x = cvt_pk_bf16(v0[0], v0[1]); w.y = cvt_pk_bf16(v0[2], v0[3]); w.z = cvt_pk_bf16(v1[0], v1[1]); w.w = cvt_pk_bf16(v1[2], v1[3]);
;                             *(u32x4*)(rowp + bj * HALF) = w; } }
.LBB0_435:
	v_readlane_b32 s62, v255, 4
	v_readlane_b32 s63, v255, 5
	v_mov_b32_e32 v0, 1.0
	s_andn2_b64 vcc, exec, s[62:63]
	v_cndmask_b32_e64 v131, 0, 1, s[62:63]
	v_cmp_ne_u32_e64 s[44:45], 1, v131
	v_mov_b32_e32 v134, 1.0
	s_cbranch_vccnz .LBB0_437
	v_ashrrev_i32_e32 v131, 31, v130
	v_lshl_add_u64 v[132:133], v[130:131], 2, s[74:75]
	flat_load_dword v131, v[132:133]
	s_waitcnt vmcnt(0) lgkmcnt(0)
	v_fmamk_f32 v131, v131, 0x3a000000, v229
	v_mul_f32_e32 v132, 0x4b800000, v131
	v_cmp_gt_f32_e32 vcc, s33, v131
	s_nop 1
	v_cndmask_b32_e32 v131, v131, v132, vcc
	v_rsq_f32_e32 v131, v131
	s_nop 0
	v_mul_f32_e32 v132, 0x45800000, v131
	v_cndmask_b32_e32 v134, v131, v132, vcc
.LBB0_437:
	v_or_b32_e32 v132, s3, v248
	v_add_u32_e32 v135, s53, v251
	v_ashrrev_i32_e32 v133, 31, v132
	v_ashrrev_i32_e32 v131, 31, v135
	v_lshl_add_u64 v[132:133], v[132:133], 1, s[24:25]
	v_mul_lo_u32 v136, s16, v131
	v_mul_lo_u32 v131, s17, v135
	v_mad_u64_u32 v[138:139], s[24:25], s16, v135, 0
	v_add3_u32 v139, v139, v136, v131
	v_lshl_add_u64 v[142:143], v[138:139], 1, v[132:133]
	v_pk_mul_f32 v[140:141], v[128:129], v[134:135] op_sel_hi:[1,0]
	v_pk_mul_f32 v[138:139], v[126:127], v[134:135] op_sel_hi:[1,0]
	v_pk_mul_f32 v[144:145], v[124:125], v[134:135] op_sel_hi:[1,0]
	v_pk_mul_f32 v[146:147], v[122:123], v[134:135] op_sel_hi:[1,0]
	v_cvt_pk_bf16_f32 v138, v138, v139
	v_cvt_pk_bf16_f32 v139, v140, v141
	s_and_b64 vcc, exec, s[44:45]
	v_cvt_pk_bf16_f32 v140, v146, v147
	v_cvt_pk_bf16_f32 v141, v144, v145
	flat_store_dwordx4 v[142:143], v[138:141]
	v_pk_mul_f32 v[144:145], v[116:117], v[134:135] op_sel_hi:[1,0]
	v_pk_mul_f32 v[146:147], v[114:115], v[134:135] op_sel_hi:[1,0]
	v_pk_mul_f32 v[140:141], v[120:121], v[134:135] op_sel_hi:[1,0]
	v_pk_mul_f32 v[138:139], v[118:119], v[134:135] op_sel_hi:[1,0]
	s_nop 0
	v_cvt_pk_bf16_f32 v138, v138, v139
	v_cvt_pk_bf16_f32 v139, v140, v141
	v_cvt_pk_bf16_f32 v140, v146, v147
	v_cvt_pk_bf16_f32 v141, v144, v145
	flat_store_dwordx4 v[142:143], v[138:141] offset:256
	s_cbranch_vccnz .LBB0_439
	v_ashrrev_i32_e32 v131, 31, v130
	v_lshl_add_u64 v[138:139], v[130:131], 2, s[74:75]
	flat_load_dword v0, v[138:139] offset:64
	s_waitcnt vmcnt(0) lgkmcnt(0)
	v_fmamk_f32 v0, v0, 0x3a000000, v229
	v_mul_f32_e32 v131, 0x4b800000, v0
	v_cmp_gt_f32_e32 vcc, s33, v0
	s_nop 1
	v_cndmask_b32_e32 v0, v0, v131, vcc
	v_rsq_f32_e32 v0, v0
	s_nop 0
	v_mul_f32_e32 v131, 0x45800000, v0
	v_cndmask_b32_e32 v0, v0, v131, vcc
.LBB0_439:
	v_or_b32_e32 v131, 16, v135
	v_mul_lo_u32 v134, s17, v131
	v_mad_u64_u32 v[138:139], s[24:25], s16, v131, 0
	v_add3_u32 v139, v139, v136, v134
	v_lshl_add_u64 v[142:143], v[138:139], 1, v[132:133]
	v_pk_mul_f32 v[140:141], v[112:113], v[0:1] op_sel_hi:[1,0]
	v_pk_mul_f32 v[138:139], v[110:111], v[0:1] op_sel_hi:[1,0]
	v_pk_mul_f32 v[144:145], v[108:109], v[0:1] op_sel_hi:[1,0]
	v_pk_mul_f32 v[146:147], v[106:107], v[0:1] op_sel_hi:[1,0]
	v_cvt_pk_bf16_f32 v138, v138, v139
	v_cvt_pk_bf16_f32 v139, v140, v141
	s_and_b64 vcc, exec, s[44:45]
	v_cvt_pk_bf16_f32 v140, v146, v147
	v_cvt_pk_bf16_f32 v141, v144, v145
	flat_store_dwordx4 v[142:143], v[138:141]
	v_pk_mul_f32 v[144:145], v[100:101], v[0:1] op_sel_hi:[1,0]
	v_pk_mul_f32 v[146:147], v[98:99], v[0:1] op_sel_hi:[1,0]
	v_pk_mul_f32 v[140:141], v[104:105], v[0:1] op_sel_hi:[1,0]
	v_pk_mul_f32 v[138:139], v[102:103], v[0:1] op_sel_hi:[1,0]
	v_mov_b32_e32 v0, 1.0
	v_mov_b32_e32 v134, 1.0
	v_cvt_pk_bf16_f32 v138, v138, v139
	v_cvt_pk_bf16_f32 v139, v140, v141
	v_cvt_pk_bf16_f32 v140, v146, v147
	v_cvt_pk_bf16_f32 v141, v144, v145
	flat_store_dwordx4 v[142:143], v[138:141] offset:256
	s_cbranch_vccnz .LBB0_441
	v_ashrrev_i32_e32 v131, 31, v130
	v_lshl_add_u64 v[138:139], v[130:131], 2, s[74:75]
	flat_load_dword v131, v[138:139] offset:128
	s_waitcnt vmcnt(0) lgkmcnt(0)
	v_fmamk_f32 v131, v131, 0x3a000000, v229
	v_mul_f32_e32 v134, 0x4b800000, v131
	v_cmp_gt_f32_e32 vcc, s33, v131
	s_nop 1
	v_cndmask_b32_e32 v131, v131, v134, vcc
	v_rsq_f32_e32 v131, v131
	s_nop 0
	v_mul_f32_e32 v134, 0x45800000, v131
	v_cndmask_b32_e32 v134, v131, v134, vcc
.LBB0_441:
	v_or_b32_e32 v131, 32, v135
	v_mul_lo_u32 v137, s17, v131
	v_mad_u64_u32 v[138:139], s[24:25], s16, v131, 0
	v_add3_u32 v139, v139, v136, v137
	v_lshl_add_u64 v[142:143], v[138:139], 1, v[132:133]
	v_pk_mul_f32 v[140:141], v[96:97], v[134:135] op_sel_hi:[1,0]
	v_pk_mul_f32 v[138:139], v[94:95], v[134:135] op_sel_hi:[1,0]
	v_pk_mul_f32 v[144:145], v[92:93], v[134:135] op_sel_hi:[1,0]
	v_pk_mul_f32 v[146:147], v[90:91], v[134:135] op_sel_hi:[1,0]
	v_cvt_pk_bf16_f32 v138, v138, v139
	v_cvt_pk_bf16_f32 v139, v140, v141
	s_and_b64 vcc, exec, s[44:45]
	v_cvt_pk_bf16_f32 v140, v146, v147
	v_cvt_pk_bf16_f32 v141, v144, v145
	flat_store_dwordx4 v[142:143], v[138:141]
	v_pk_mul_f32 v[144:145], v[84:85], v[134:135] op_sel_hi:[1,0]
	v_pk_mul_f32 v[146:147], v[82:83], v[134:135] op_sel_hi:[1,0]
	v_pk_mul_f32 v[140:141], v[88:89], v[134:135] op_sel_hi:[1,0]
	v_pk_mul_f32 v[138:139], v[86:87], v[134:135] op_sel_hi:[1,0]
	s_nop 0
	v_cvt_pk_bf16_f32 v138, v138, v139
	v_cvt_pk_bf16_f32 v139, v140, v141
	v_cvt_pk_bf16_f32 v140, v146, v147
	v_cvt_pk_bf16_f32 v141, v144, v145
	flat_store_dwordx4 v[142:143], v[138:141] offset:256
	s_cbranch_vccnz .LBB0_443
	v_ashrrev_i32_e32 v131, 31, v130
	v_lshl_add_u64 v[138:139], v[130:131], 2, s[74:75]
	flat_load_dword v0, v[138:139] offset:192
	s_waitcnt vmcnt(0) lgkmcnt(0)
	v_fmamk_f32 v0, v0, 0x3a000000, v229
	v_mul_f32_e32 v131, 0x4b800000, v0
	v_cmp_gt_f32_e32 vcc, s33, v0
	s_nop 1
	v_cndmask_b32_e32 v0, v0, v131, vcc
	v_rsq_f32_e32 v0, v0
	s_nop 0
	v_mul_f32_e32 v131, 0x45800000, v0
	v_cndmask_b32_e32 v0, v0, v131, vcc
; DI unsigned cvt_pk_bf16(float lo, float hi) { unsigned r; asm volatile("v_cvt_pk_bf16_f32 %0, %1, %2" : "=v"(r) : "v"(lo), "v"(hi)); return r; }
;     DI void operator()(const f32x4 (&acc)[2][2][4][2], const Unit& u, int wr, int wc, int fr, int fq) const {
;     ...
;                 const int rloc = wr * 64 + fr, col0 = colb + wc * 32 + 8 * fq;
; #pragma unroll
;                 for (int ai = 0; ai < 2; ++ai)
; #pragma unroll
;                     for (int m = 0; m < 4; ++m) { bf16_t* rowp = base + (size_t)(rowb + rloc + ai * HALF + m * 16) * ld + col0;
;                         const float rs_ = ss_in ? rsqrtf(ss_in[row0 + ai * HALF + m * 16] * (1.f / DM) + EPS) : 1.f;
; #pragma unroll
;                         for (int bj = 0; bj < 2; ++bj) { const f32x4 v0 = acc[ai][bj][m][0] * rs_, v1 = acc[ai][bj][m][1] * rs_;
;                             u32x4 w; w.x = cvt_pk_bf16(v0[0], v0[1]); w.y = cvt_pk_bf16(v0[2], v0[3]); w.z = cvt_pk_bf16(v1[0], v1[1]); w.w = cvt_pk_bf16(v1[2], v1[3]);
;                             *(u32x4*)(rowp + bj * HALF) = w; } }
.LBB0_443:
	v_or_b32_e32 v131, 48, v135
	v_mul_lo_u32 v134, s17, v131
	v_mad_u64_u32 v[138:139], s[24:25], s16, v131, 0
	v_add3_u32 v139, v139, v136, v134
	v_lshl_add_u64 v[140:141], v[138:139], 1, v[132:133]
	v_pk_mul_f32 v[138:139], v[80:81], v[0:1] op_sel_hi:[1,0]
	v_pk_mul_f32 v[136:137], v[78:79], v[0:1] op_sel_hi:[1,0]
	v_pk_mul_f32 v[142:143], v[76:77], v[0:1] op_sel_hi:[1,0]
	v_pk_mul_f32 v[144:145], v[74:75], v[0:1] op_sel_hi:[1,0]
	v_cvt_pk_bf16_f32 v136, v136, v137
	v_cvt_pk_bf16_f32 v137, v138, v139
	s_and_b64 vcc, exec, s[44:45]
	v_cvt_pk_bf16_f32 v138, v144, v145
	v_cvt_pk_bf16_f32 v139, v142, v143
	flat_store_dwordx4 v[140:141], v[136:139]
	v_pk_mul_f32 v[142:143], v[68:69], v[0:1] op_sel_hi:[1,0]
	v_pk_mul_f32 v[144:145], v[66:67], v[0:1] op_sel_hi:[1,0]
	v_pk_mul_f32 v[138:139], v[72:73], v[0:1] op_sel_hi:[1,0]
	v_pk_mul_f32 v[136:137], v[70:71], v[0:1] op_sel_hi:[1,0]
	v_mov_b32_e32 v0, 1.0
	v_mov_b32_e32 v134, 1.0
	v_cvt_pk_bf16_f32 v136, v136, v137
	v_cvt_pk_bf16_f32 v137, v138, v139
	v_cvt_pk_bf16_f32 v138, v144, v145
	v_cvt_pk_bf16_f32 v139, v142, v143
	flat_store_dwordx4 v[140:141], v[136:139] offset:256
	s_cbranch_vccnz .LBB0_445
	v_ashrrev_i32_e32 v131, 31, v130
	v_lshl_add_u64 v[136:137], v[130:131], 2, s[74:75]
	flat_load_dword v131, v[136:137] offset:512
	s_waitcnt vmcnt(0) lgkmcnt(0)
	v_fmamk_f32 v131, v131, 0x3a000000, v229
	v_mul_f32_e32 v134, 0x4b800000, v131
	v_cmp_gt_f32_e32 vcc, s33, v131
	s_nop 1
	v_cndmask_b32_e32 v131, v131, v134, vcc
	v_rsq_f32_e32 v131, v131
	s_nop 0
	v_mul_f32_e32 v134, 0x45800000, v131
	v_cndmask_b32_e32 v134, v131, v134, vcc
.LBB0_445:
	v_add_u32_e32 v131, 0x80, v135
	v_ashrrev_i32_e32 v136, 31, v131
	v_mul_lo_u32 v138, s16, v136
	v_mul_lo_u32 v139, s17, v131
	v_mad_u64_u32 v[136:137], s[24:25], s16, v131, 0
	v_add3_u32 v137, v137, v138, v139
	v_lshl_add_u64 v[140:141], v[136:137], 1, v[132:133]
	v_pk_mul_f32 v[138:139], v[64:65], v[134:135] op_sel_hi:[1,0]
	v_pk_mul_f32 v[136:137], v[62:63], v[134:135] op_sel_hi:[1,0]
	v_pk_mul_f32 v[142:143], v[60:61], v[134:135] op_sel_hi:[1,0]
	v_pk_mul_f32 v[144:145], v[58:59], v[134:135] op_sel_hi:[1,0]
	v_cvt_pk_bf16_f32 v136, v136, v137
	v_cvt_pk_bf16_f32 v137, v138, v139
	s_and_b64 vcc, exec, s[44:45]
	v_cvt_pk_bf16_f32 v138, v144, v145
	v_cvt_pk_bf16_f32 v139, v142, v143
	flat_store_dwordx4 v[140:141], v[136:139]
	v_pk_mul_f32 v[142:143], v[52:53], v[134:135] op_sel_hi:[1,0]
	v_pk_mul_f32 v[144:145], v[50:51], v[134:135] op_sel_hi:[1,0]
	v_pk_mul_f32 v[138:139], v[56:57], v[134:135] op_sel_hi:[1,0]
	v_pk_mul_f32 v[136:137], v[54:55], v[134:135] op_sel_hi:[1,0]
	s_nop 0
	v_cvt_pk_bf16_f32 v136, v136, v137
	v_cvt_pk_bf16_f32 v137, v138, v139
	v_cvt_pk_bf16_f32 v138, v144, v145
	v_cvt_pk_bf16_f32 v139, v142, v143
	flat_store_dwordx4 v[140:141], v[136:139] offset:256
	s_cbranch_vccnz .LBB0_447
	v_ashrrev_i32_e32 v131, 31, v130
	v_lshl_add_u64 v[136:137], v[130:131], 2, s[74:75]
	flat_load_dword v0, v[136:137] offset:576
	s_waitcnt vmcnt(0) lgkmcnt(0)
	v_fmamk_f32 v0, v0, 0x3a000000, v229
	v_mul_f32_e32 v131, 0x4b800000, v0
	v_cmp_gt_f32_e32 vcc, s33, v0
	s_nop 1
	v_cndmask_b32_e32 v0, v0, v131, vcc
	v_rsq_f32_e32 v0, v0
	s_nop 0
	v_mul_f32_e32 v131, 0x45800000, v0
	v_cndmask_b32_e32 v0, v0, v131, vcc
.LBB0_447:
	v_add_u32_e32 v131, 0x90, v135
	v_ashrrev_i32_e32 v134, 31, v131
	v_mul_lo_u32 v134, s16, v134
	v_mul_lo_u32 v138, s17, v131
	v_mad_u64_u32 v[136:137], s[24:25], s16, v131, 0
	v_add3_u32 v137, v137, v134, v138
	v_lshl_add_u64 v[140:141], v[136:137], 1, v[132:133]
	v_pk_mul_f32 v[138:139], v[48:49], v[0:1] op_sel_hi:[1,0]
	v_pk_mul_f32 v[136:137], v[46:47], v[0:1] op_sel_hi:[1,0]
	v_pk_mul_f32 v[142:143], v[44:45], v[0:1] op_sel_hi:[1,0]
	v_pk_mul_f32 v[144:145], v[42:43], v[0:1] op_sel_hi:[1,0]
	v_cvt_pk_bf16_f32 v136, v136, v137
	v_cvt_pk_bf16_f32 v137, v138, v139
	s_and_b64 vcc, exec, s[44:45]
	v_cvt_pk_bf16_f32 v138, v144, v145
	v_cvt_pk_bf16_f32 v139, v142, v143
	flat_store_dwordx4 v[140:141], v[136:139]
	v_pk_mul_f32 v[142:143], v[36:37], v[0:1] op_sel_hi:[1,0]
	v_pk_mul_f32 v[144:145], v[34:35], v[0:1] op_sel_hi:[1,0]
	v_pk_mul_f32 v[138:139], v[40:41], v[0:1] op_sel_hi:[1,0]
	v_pk_mul_f32 v[136:137], v[38:39], v[0:1] op_sel_hi:[1,0]
	v_mov_b32_e32 v0, 1.0
	v_mov_b32_e32 v134, 1.0
	v_cvt_pk_bf16_f32 v136, v136, v137
	v_cvt_pk_bf16_f32 v137, v138, v139
	v_cvt_pk_bf16_f32 v138, v144, v145
	v_cvt_pk_bf16_f32 v139, v142, v143
	flat_store_dwordx4 v[140:141], v[136:139] offset:256
	s_cbranch_vccnz .LBB0_449
	v_ashrrev_i32_e32 v131, 31, v130
	v_lshl_add_u64 v[136:137], v[130:131], 2, s[74:75]
	flat_load_dword v131, v[136:137] offset:640
	s_waitcnt vmcnt(0) lgkmcnt(0)
	v_fmamk_f32 v131, v131, 0x3a000000, v229
	v_mul_f32_e32 v134, 0x4b800000, v131
	v_cmp_gt_f32_e32 vcc, s33, v131
	s_nop 1
	v_cndmask_b32_e32 v131, v131, v134, vcc
	v_rsq_f32_e32 v131, v131
	s_nop 0
	v_mul_f32_e32 v134, 0x45800000, v131
	v_cndmask_b32_e32 v134, v131, v134, vcc
.LBB0_449:
	v_add_u32_e32 v131, 0xa0, v135
	v_ashrrev_i32_e32 v136, 31, v131
	v_mul_lo_u32 v138, s16, v136
	v_mul_lo_u32 v139, s17, v131
	v_mad_u64_u32 v[136:137], s[24:25], s16, v131, 0
	v_add3_u32 v137, v137, v138, v139
	v_lshl_add_u64 v[140:141], v[136:137], 1, v[132:133]
	v_pk_mul_f32 v[138:139], v[32:33], v[134:135] op_sel_hi:[1,0]
	v_pk_mul_f32 v[136:137], v[30:31], v[134:135] op_sel_hi:[1,0]
	v_pk_mul_f32 v[142:143], v[28:29], v[134:135] op_sel_hi:[1,0]
	v_pk_mul_f32 v[144:145], v[26:27], v[134:135] op_sel_hi:[1,0]
	v_cvt_pk_bf16_f32 v136, v136, v137
	v_cvt_pk_bf16_f32 v137, v138, v139
	s_and_b64 vcc, exec, s[44:45]
	v_cvt_pk_bf16_f32 v138, v144, v145
	v_cvt_pk_bf16_f32 v139, v142, v143
	flat_store_dwordx4 v[140:141], v[136:139]
	v_pk_mul_f32 v[142:143], v[20:21], v[134:135] op_sel_hi:[1,0]
	v_pk_mul_f32 v[144:145], v[18:19], v[134:135] op_sel_hi:[1,0]
	v_pk_mul_f32 v[138:139], v[24:25], v[134:135] op_sel_hi:[1,0]
	v_pk_mul_f32 v[136:137], v[22:23], v[134:135] op_sel_hi:[1,0]
	s_nop 0
	v_cvt_pk_bf16_f32 v136, v136, v137
	v_cvt_pk_bf16_f32 v137, v138, v139
	v_cvt_pk_bf16_f32 v138, v144, v145
	v_cvt_pk_bf16_f32 v139, v142, v143
	flat_store_dwordx4 v[140:141], v[136:139] offset:256
	s_cbranch_vccnz .LBB0_451
	v_ashrrev_i32_e32 v131, 31, v130
	v_lshl_add_u64 v[136:137], v[130:131], 2, s[74:75]
	flat_load_dword v0, v[136:137] offset:704
	s_waitcnt vmcnt(0) lgkmcnt(0)
	v_fmamk_f32 v0, v0, 0x3a000000, v229
	v_mul_f32_e32 v131, 0x4b800000, v0
	v_cmp_gt_f32_e32 vcc, s33, v0
	s_nop 1
	v_cndmask_b32_e32 v0, v0, v131, vcc
	v_rsq_f32_e32 v0, v0
	s_nop 0
	v_mul_f32_e32 v131, 0x45800000, v0
	v_cndmask_b32_e32 v0, v0, v131, vcc

; DI unsigned f2bf(float f) { unsigned u = __builtin_bit_cast(unsigned, f); return (u + 0x7fffu + ((u >> 16) & 1u)) >> 16; }
;     DI void operator()(const f32x4 (&acc)[2][2][4][2], const Unit& u, int wr, int wc, int fr, int fq) const {
;     ...
;                 bf16_t* base = ((u.pm * BM) >> 13) ? VTS1 : VTS0; const int ldt = SEQ, rowi = ((u.pm * BM) & (SEQ - 1)) + wr * 64 + fr, col0 = (u.pn - vt_lo) * BM + wc * 32 + 8 * fq;
; #pragma unroll
;                 for (int ai = 0; ai < 2; ++ai)
; #pragma unroll
;                     for (int m = 0; m < 4; ++m) { const int row = rowi + ai * HALF + m * 16;
;                         const float rs_ = ss_in ? rsqrtf(ss_in[row0 + ai * HALF + m * 16] * (1.f / DM) + EPS) : 1.f;
; #pragma unroll
;                         for (int bj = 0; bj < 2; ++bj)
; #pragma unroll
;                             for (int n = 0; n < 2; ++n)
; #pragma unroll
;                                 for (int j = 0; j < 4; ++j) base[(size_t)(col0 + bj * HALF + 4 * n + j) * ldt + row] = (bf16_t)f2bf(acc[ai][bj][m][n][j] * rs_); }
.LBB0_452:
	s_and_b64 vcc, exec, s[24:25]
	s_cbranch_vccz .LBB0_470
	v_readlane_b32 s16, v255, 4
	v_readlane_b32 s17, v255, 5
	v_mov_b32_e32 v164, 1.0
	s_andn2_b64 vcc, exec, s[16:17]
	v_cndmask_b32_e64 v0, 0, 1, s[16:17]
	v_cmp_ne_u32_e64 s[44:45], 1, v0
	v_ashrrev_i32_e32 v131, 31, v130
	v_mov_b32_e32 v162, 1.0
	s_cbranch_vccnz .LBB0_455
	v_lshl_add_u64 v[132:133], v[130:131], 2, s[74:75]
	flat_load_dword v0, v[132:133]
	s_waitcnt vmcnt(0) lgkmcnt(0)
	v_fmamk_f32 v0, v0, 0x3a000000, v229
	v_mul_f32_e32 v132, 0x4b800000, v0
	v_cmp_gt_f32_e32 vcc, s33, v0
	s_nop 1
	v_cndmask_b32_e32 v0, v0, v132, vcc
	v_rsq_f32_e32 v0, v0
	s_nop 0
	v_mul_f32_e32 v132, 0x45800000, v0
	v_cndmask_b32_e32 v162, v0, v132, vcc
.LBB0_455:
	v_readlane_b32 s16, v255, 2
	s_cmp_lt_u32 s76, 32
	v_readlane_b32 s17, v255, 3
	s_cselect_b32 s3, s17, s99
	s_cselect_b32 s13, s16, s98
	v_mov_b32_e32 v133, s3
	s_and_b32 s3, s12, 0x1f00
	v_add_u32_e32 v134, s3, v251
	v_mov_b32_e32 v132, s13
	v_ashrrev_i32_e32 v135, 31, v134
	v_mul_f32_e32 v0, v126, v162
	v_lshl_add_u64 v[132:133], v[134:135], 1, v[132:133]
	v_bfe_u32 v134, v0, 16, 1
	v_add3_u32 v0, v0, v134, s92
	v_lshlrev_b32_e32 v134, 14, v248
	v_lshl_or_b32 v166, s8, 22, v134
	v_mov_b32_e32 v167, v1
	v_lshl_add_u64 v[134:135], v[132:133], 0, v[166:167]
	flat_store_short_d16_hi v[134:135], v0
	v_mul_f32_e32 v0, v127, v162
	v_bfe_u32 v136, v0, 16, 1
	v_add3_u32 v138, v0, v136, s92
	v_or_b32_e32 v0, 0x4000, v166
	v_lshl_add_u64 v[136:137], v[132:133], 0, v[0:1]
	flat_store_short_d16_hi v[136:137], v138
	v_mul_f32_e32 v136, v128, v162
	v_bfe_u32 v137, v136, 16, 1
	v_add3_u32 v140, v136, v137, s92
	v_or_b32_e32 v136, 0x8000, v166
	v_mov_b32_e32 v137, v1
	v_lshl_add_u64 v[138:139], v[132:133], 0, v[136:137]
	flat_store_short_d16_hi v[138:139], v140
	v_mul_f32_e32 v138, v129, v162
	v_bfe_u32 v139, v138, 16, 1
	v_add3_u32 v142, v138, v139, s92
	v_or_b32_e32 v138, 0xc000, v166
	v_mov_b32_e32 v139, v1
	v_lshl_add_u64 v[140:141], v[132:133], 0, v[138:139]
	flat_store_short_d16_hi v[140:141], v142
	v_mul_f32_e32 v140, v122, v162
	v_bfe_u32 v141, v140, 16, 1
	v_add3_u32 v144, v140, v141, s92
	v_or_b32_e32 v140, 0x10000, v166
	v_mov_b32_e32 v141, v1
	v_lshl_add_u64 v[142:143], v[132:133], 0, v[140:141]
	flat_store_short_d16_hi v[142:143], v144
	v_mul_f32_e32 v142, v123, v162
	v_bfe_u32 v143, v142, 16, 1
	v_add3_u32 v146, v142, v143, s92
	v_or_b32_e32 v142, 0x14000, v166
	v_mov_b32_e32 v143, v1
	v_lshl_add_u64 v[144:145], v[132:133], 0, v[142:143]
	flat_store_short_d16_hi v[144:145], v146
	v_mul_f32_e32 v144, v124, v162
	v_bfe_u32 v145, v144, 16, 1
	v_add3_u32 v148, v144, v145, s92
	v_or_b32_e32 v144, 0x18000, v166
	v_mov_b32_e32 v145, v1
	v_lshl_add_u64 v[146:147], v[132:133], 0, v[144:145]
	flat_store_short_d16_hi v[146:147], v148
	v_mul_f32_e32 v146, v125, v162
	v_bfe_u32 v147, v146, 16, 1
	v_add3_u32 v150, v146, v147, s92
	v_or_b32_e32 v146, 0x1c000, v166
	v_mov_b32_e32 v147, v1
	v_lshl_add_u64 v[148:149], v[132:133], 0, v[146:147]
	flat_store_short_d16_hi v[148:149], v150
	v_mul_f32_e32 v148, v118, v162
	v_bfe_u32 v149, v148, 16, 1
	v_add3_u32 v152, v148, v149, s92
	v_or_b32_e32 v148, 0x200000, v166
	v_mov_b32_e32 v149, v1
	v_lshl_add_u64 v[150:151], v[132:133], 0, v[148:149]
	flat_store_short_d16_hi v[150:151], v152
	v_mul_f32_e32 v150, v119, v162
	v_bfe_u32 v151, v150, 16, 1
	v_add3_u32 v154, v150, v151, s92
	v_or_b32_e32 v150, 0x204000, v166
	v_mov_b32_e32 v151, v1
	v_lshl_add_u64 v[152:153], v[132:133], 0, v[150:151]
	flat_store_short_d16_hi v[152:153], v154
	v_mul_f32_e32 v152, v120, v162
	v_bfe_u32 v153, v152, 16, 1
	v_add3_u32 v156, v152, v153, s92
	v_or_b32_e32 v152, 0x208000, v166
	v_mov_b32_e32 v153, v1
	v_lshl_add_u64 v[154:155], v[132:133], 0, v[152:153]
	flat_store_short_d16_hi v[154:155], v156
	v_mul_f32_e32 v154, v121, v162
	v_bfe_u32 v155, v154, 16, 1
	v_add3_u32 v158, v154, v155, s92
	v_or_b32_e32 v154, 0x20c000, v166
	v_mov_b32_e32 v155, v1
	v_lshl_add_u64 v[156:157], v[132:133], 0, v[154:155]
	flat_store_short_d16_hi v[156:157], v158
	v_mul_f32_e32 v156, v114, v162
	v_bfe_u32 v157, v156, 16, 1
	v_add3_u32 v160, v156, v157, s92
	v_or_b32_e32 v156, 0x210000, v166
	v_mov_b32_e32 v157, v1
	v_lshl_add_u64 v[158:159], v[132:133], 0, v[156:157]
	flat_store_short_d16_hi v[158:159], v160
	v_mul_f32_e32 v158, v115, v162
	v_bfe_u32 v159, v158, 16, 1
	v_add3_u32 v163, v158, v159, s92
	v_or_b32_e32 v158, 0x214000, v166
	v_mov_b32_e32 v159, v1
	v_lshl_add_u64 v[160:161], v[132:133], 0, v[158:159]
	flat_store_short_d16_hi v[160:161], v163
	v_mul_f32_e32 v160, v116, v162
	v_bfe_u32 v161, v160, 16, 1
	v_add3_u32 v163, v160, v161, s92
	v_or_b32_e32 v160, 0x218000, v166
	v_mov_b32_e32 v161, v1
	v_lshl_add_u64 v[168:169], v[132:133], 0, v[160:161]
	v_mul_f32_e32 v162, v117, v162
	flat_store_short_d16_hi v[168:169], v163
	v_bfe_u32 v163, v162, 16, 1
	v_add3_u32 v165, v162, v163, s92
	v_or_b32_e32 v162, 0x21c000, v166
	v_mov_b32_e32 v163, v1
	v_lshl_add_u64 v[166:167], v[132:133], 0, v[162:163]
	s_and_b64 vcc, exec, s[44:45]
	flat_store_short_d16_hi v[166:167], v165
	s_cbranch_vccnz .LBB0_457
	v_lshl_add_u64 v[164:165], v[130:131], 2, s[74:75]
	flat_load_dword v164, v[164:165] offset:64
	s_waitcnt vmcnt(0) lgkmcnt(0)
	v_fmamk_f32 v164, v164, 0x3a000000, v229
	v_mul_f32_e32 v165, 0x4b800000, v164
	v_cmp_gt_f32_e32 vcc, s33, v164
	s_nop 1
	v_cndmask_b32_e32 v164, v164, v165, vcc
	v_rsq_f32_e32 v164, v164
	s_nop 0
	v_mul_f32_e32 v165, 0x45800000, v164
	v_cndmask_b32_e32 v164, v164, v165, vcc
; DI unsigned f2bf(float f) { unsigned u = __builtin_bit_cast(unsigned, f); return (u + 0x7fffu + ((u >> 16) & 1u)) >> 16; }
;     DI void operator()(const f32x4 (&acc)[2][2][4][2], const Unit& u, int wr, int wc, int fr, int fq) const {
;     ...
;                 bf16_t* base = ((u.pm * BM) >> 13) ? VTS1 : VTS0; const int ldt = SEQ, rowi = ((u.pm * BM) & (SEQ - 1)) + wr * 64 + fr, col0 = (u.pn - vt_lo) * BM + wc * 32 + 8 * fq;
; #pragma unroll
;                 for (int ai = 0; ai < 2; ++ai)
; #pragma unroll
;                     for (int m = 0; m < 4; ++m) { const int row = rowi + ai * HALF + m * 16;
;                         const float rs_ = ss_in ? rsqrtf(ss_in[row0 + ai * HALF + m * 16] * (1.f / DM) + EPS) : 1.f;
; #pragma unroll
;                         for (int bj = 0; bj < 2; ++bj)
; #pragma unroll
;                             for (int n = 0; n < 2; ++n)
; #pragma unroll
;                                 for (int j = 0; j < 4; ++j) base[(size_t)(col0 + bj * HALF + 4 * n + j) * ldt + row] = (bf16_t)f2bf(acc[ai][bj][m][n][j] * rs_); }
.LBB0_457:
	v_mul_f32_e32 v165, v110, v164
	v_bfe_u32 v168, v165, 16, 1
	v_add3_u32 v165, v165, v168, s92
	flat_store_short_d16_hi v[134:135], v165 offset:32
	v_mul_f32_e32 v165, v111, v164
	v_lshl_add_u64 v[166:167], v[132:133], 0, 32
	v_bfe_u32 v168, v165, 16, 1
	v_add3_u32 v165, v165, v168, s92
	v_lshl_add_u64 v[168:169], v[166:167], 0, v[0:1]
	flat_store_short_d16_hi v[168:169], v165
	v_mul_f32_e32 v165, v112, v164
	v_bfe_u32 v168, v165, 16, 1
	v_add3_u32 v165, v165, v168, s92
	v_lshl_add_u64 v[168:169], v[166:167], 0, v[136:137]
	flat_store_short_d16_hi v[168:169], v165
	v_mul_f32_e32 v165, v113, v164
	v_bfe_u32 v168, v165, 16, 1
	v_add3_u32 v165, v165, v168, s92
	v_lshl_add_u64 v[168:169], v[166:167], 0, v[138:139]
	flat_store_short_d16_hi v[168:169], v165
	v_mul_f32_e32 v165, v106, v164
	v_bfe_u32 v168, v165, 16, 1
	v_add3_u32 v165, v165, v168, s92
	v_lshl_add_u64 v[168:169], v[166:167], 0, v[140:141]
	flat_store_short_d16_hi v[168:169], v165
	v_mul_f32_e32 v165, v107, v164
	v_bfe_u32 v168, v165, 16, 1
	v_add3_u32 v165, v165, v168, s92
	v_lshl_add_u64 v[168:169], v[166:167], 0, v[142:143]
	flat_store_short_d16_hi v[168:169], v165
	v_mul_f32_e32 v165, v108, v164
	v_bfe_u32 v168, v165, 16, 1
	v_add3_u32 v165, v165, v168, s92
	v_lshl_add_u64 v[168:169], v[166:167], 0, v[144:145]
	flat_store_short_d16_hi v[168:169], v165
	v_mul_f32_e32 v165, v109, v164
	v_bfe_u32 v168, v165, 16, 1
	v_add3_u32 v165, v165, v168, s92
	v_lshl_add_u64 v[168:169], v[166:167], 0, v[146:147]
	flat_store_short_d16_hi v[168:169], v165
	v_mul_f32_e32 v165, v102, v164
	v_bfe_u32 v168, v165, 16, 1
	v_add3_u32 v165, v165, v168, s92
	v_lshl_add_u64 v[168:169], v[166:167], 0, v[148:149]
	flat_store_short_d16_hi v[168:169], v165
	v_mul_f32_e32 v165, v103, v164
	v_bfe_u32 v168, v165, 16, 1
	v_add3_u32 v165, v165, v168, s92
	v_lshl_add_u64 v[168:169], v[166:167], 0, v[150:151]
	flat_store_short_d16_hi v[168:169], v165
	v_mul_f32_e32 v165, v104, v164
	v_bfe_u32 v168, v165, 16, 1
	v_add3_u32 v165, v165, v168, s92
	v_lshl_add_u64 v[168:169], v[166:167], 0, v[152:153]
	flat_store_short_d16_hi v[168:169], v165
	v_mul_f32_e32 v165, v105, v164
	v_bfe_u32 v168, v165, 16, 1
	v_add3_u32 v165, v165, v168, s92
	v_lshl_add_u64 v[168:169], v[166:167], 0, v[154:155]
	flat_store_short_d16_hi v[168:169], v165
	v_mul_f32_e32 v165, v98, v164
	v_bfe_u32 v168, v165, 16, 1
	v_add3_u32 v165, v165, v168, s92
	v_lshl_add_u64 v[168:169], v[166:167], 0, v[156:157]
	flat_store_short_d16_hi v[168:169], v165
	v_mul_f32_e32 v165, v99, v164
	v_bfe_u32 v168, v165, 16, 1
	v_add3_u32 v165, v165, v168, s92
	v_lshl_add_u64 v[168:169], v[166:167], 0, v[158:159]
	flat_store_short_d16_hi v[168:169], v165
	v_mul_f32_e32 v165, v100, v164
	v_bfe_u32 v168, v165, 16, 1
	v_add3_u32 v165, v165, v168, s92
	v_lshl_add_u64 v[168:169], v[166:167], 0, v[160:161]
	v_mul_f32_e32 v164, v101, v164
	flat_store_short_d16_hi v[168:169], v165
	v_bfe_u32 v165, v164, 16, 1
	v_add3_u32 v168, v164, v165, s92
	v_lshl_add_u64 v[164:165], v[166:167], 0, v[162:163]
	flat_store_short_d16_hi v[164:165], v168
	v_mov_b32_e32 v164, 1.0
	s_and_b64 vcc, exec, s[44:45]
	v_mov_b32_e32 v165, 1.0
	s_cbranch_vccnz .LBB0_459
	v_lshl_add_u64 v[166:167], v[130:131], 2, s[74:75]
	flat_load_dword v165, v[166:167] offset:128
	s_waitcnt vmcnt(0) lgkmcnt(0)
	v_fmamk_f32 v165, v165, 0x3a000000, v229
	v_mul_f32_e32 v166, 0x4b800000, v165
	v_cmp_gt_f32_e32 vcc, s33, v165
	s_nop 1
	v_cndmask_b32_e32 v165, v165, v166, vcc
	v_rsq_f32_e32 v165, v165
	s_nop 0
	v_mul_f32_e32 v166, 0x45800000, v165
	v_cndmask_b32_e32 v165, v165, v166, vcc
.LBB0_459:
	v_mul_f32_e32 v168, v94, v165
	v_bfe_u32 v169, v168, 16, 1
	v_add3_u32 v168, v168, v169, s92
	flat_store_short_d16_hi v[134:135], v168 offset:64
	v_mul_f32_e32 v168, v95, v165
	v_lshl_add_u64 v[166:167], v[132:133], 0, 64
	v_bfe_u32 v169, v168, 16, 1
	v_add3_u32 v170, v168, v169, s92
	v_lshl_add_u64 v[168:169], v[166:167], 0, v[0:1]
	flat_store_short_d16_hi v[168:169], v170
	v_mul_f32_e32 v168, v96, v165
	v_bfe_u32 v169, v168, 16, 1
	v_add3_u32 v170, v168, v169, s92
	v_lshl_add_u64 v[168:169], v[166:167], 0, v[136:137]
	flat_store_short_d16_hi v[168:169], v170
	v_mul_f32_e32 v168, v97, v165
	v_bfe_u32 v169, v168, 16, 1
	v_add3_u32 v170, v168, v169, s92
	v_lshl_add_u64 v[168:169], v[166:167], 0, v[138:139]
	flat_store_short_d16_hi v[168:169], v170
	v_mul_f32_e32 v168, v90, v165
	v_bfe_u32 v169, v168, 16, 1
	v_add3_u32 v170, v168, v169, s92
	v_lshl_add_u64 v[168:169], v[166:167], 0, v[140:141]
	flat_store_short_d16_hi v[168:169], v170
	v_mul_f32_e32 v168, v91, v165
	v_bfe_u32 v169, v168, 16, 1
	v_add3_u32 v170, v168, v169, s92
	v_lshl_add_u64 v[168:169], v[166:167], 0, v[142:143]
	flat_store_short_d16_hi v[168:169], v170
	v_mul_f32_e32 v168, v92, v165
	v_bfe_u32 v169, v168, 16, 1
	v_add3_u32 v170, v168, v169, s92
	v_lshl_add_u64 v[168:169], v[166:167], 0, v[144:145]
	flat_store_short_d16_hi v[168:169], v170
	v_mul_f32_e32 v168, v93, v165
	v_bfe_u32 v169, v168, 16, 1
	v_add3_u32 v170, v168, v169, s92
	v_lshl_add_u64 v[168:169], v[166:167], 0, v[146:147]
	flat_store_short_d16_hi v[168:169], v170
	v_mul_f32_e32 v168, v86, v165
	v_bfe_u32 v169, v168, 16, 1
	v_add3_u32 v170, v168, v169, s92
	v_lshl_add_u64 v[168:169], v[166:167], 0, v[148:149]
	flat_store_short_d16_hi v[168:169], v170
	v_mul_f32_e32 v168, v87, v165
	v_bfe_u32 v169, v168, 16, 1
	v_add3_u32 v170, v168, v169, s92
	v_lshl_add_u64 v[168:169], v[166:167], 0, v[150:151]
	flat_store_short_d16_hi v[168:169], v170
	v_mul_f32_e32 v168, v88, v165
	v_bfe_u32 v169, v168, 16, 1
	v_add3_u32 v170, v168, v169, s92
	v_lshl_add_u64 v[168:169], v[166:167], 0, v[152:153]
	flat_store_short_d16_hi v[168:169], v170
	v_mul_f32_e32 v168, v89, v165
	v_bfe_u32 v169, v168, 16, 1
	v_add3_u32 v170, v168, v169, s92
	v_lshl_add_u64 v[168:169], v[166:167], 0, v[154:155]
	flat_store_short_d16_hi v[168:169], v170
	v_mul_f32_e32 v168, v82, v165
	v_bfe_u32 v169, v168, 16, 1
	v_add3_u32 v170, v168, v169, s92
	v_lshl_add_u64 v[168:169], v[166:167], 0, v[156:157]
	flat_store_short_d16_hi v[168:169], v170
	v_mul_f32_e32 v168, v83, v165
	v_bfe_u32 v169, v168, 16, 1
	v_add3_u32 v170, v168, v169, s92
	v_lshl_add_u64 v[168:169], v[166:167], 0, v[158:159]
	flat_store_short_d16_hi v[168:169], v170
	v_mul_f32_e32 v168, v84, v165
	v_bfe_u32 v169, v168, 16, 1
	v_add3_u32 v170, v168, v169, s92
	v_lshl_add_u64 v[168:169], v[166:167], 0, v[160:161]
	v_mul_f32_e32 v165, v85, v165
	flat_store_short_d16_hi v[168:169], v170
	v_bfe_u32 v168, v165, 16, 1
	v_add3_u32 v165, v165, v168, s92
	v_lshl_add_u64 v[166:167], v[166:167], 0, v[162:163]
	s_and_b64 vcc, exec, s[44:45]
	flat_store_short_d16_hi v[166:167], v165
	s_cbranch_vccnz .LBB0_461
; DI unsigned f2bf(float f) { unsigned u = __builtin_bit_cast(unsigned, f); return (u + 0x7fffu + ((u >> 16) & 1u)) >> 16; }
;     DI void operator()(const f32x4 (&acc)[2][2][4][2], const Unit& u, int wr, int wc, int fr, int fq) const {
;     ...
;                 bf16_t* base = ((u.pm * BM) >> 13) ? VTS1 : VTS0; const int ldt = SEQ, rowi = ((u.pm * BM) & (SEQ - 1)) + wr * 64 + fr, col0 = (u.pn - vt_lo) * BM + wc * 32 + 8 * fq;
; #pragma unroll
;                 for (int ai = 0; ai < 2; ++ai)
; #pragma unroll
;                     for (int m = 0; m < 4; ++m) { const int row = rowi + ai * HALF + m * 16;
;                         const float rs_ = ss_in ? rsqrtf(ss_in[row0 + ai * HALF + m * 16] * (1.f / DM) + EPS) : 1.f;
; #pragma unroll
;                         for (int bj = 0; bj < 2; ++bj)
; #pragma unroll
;                             for (int n = 0; n < 2; ++n)
; #pragma unroll
;                                 for (int j = 0; j < 4; ++j) base[(size_t)(col0 + bj * HALF + 4 * n + j) * ldt + row] = (bf16_t)f2bf(acc[ai][bj][m][n][j] * rs_); }
	v_lshl_add_u64 v[164:165], v[130:131], 2, s[74:75]
	flat_load_dword v164, v[164:165] offset:192
	s_waitcnt vmcnt(0) lgkmcnt(0)
	v_fmamk_f32 v164, v164, 0x3a000000, v229
	v_mul_f32_e32 v165, 0x4b800000, v164
	v_cmp_gt_f32_e32 vcc, s33, v164
	s_nop 1
	v_cndmask_b32_e32 v164, v164, v165, vcc
	v_rsq_f32_e32 v164, v164
	s_nop 0
	v_mul_f32_e32 v165, 0x45800000, v164
	v_cndmask_b32_e32 v164, v164, v165, vcc
.LBB0_461:
	v_mul_f32_e32 v165, v78, v164
	v_bfe_u32 v168, v165, 16, 1
	v_add3_u32 v165, v165, v168, s92
	s_mov_b64 s[12:13], 0x60
	flat_store_short_d16_hi v[134:135], v165 offset:96
	v_mul_f32_e32 v165, v79, v164
	v_lshl_add_u64 v[166:167], v[132:133], 0, s[12:13]
	v_bfe_u32 v168, v165, 16, 1
	v_add3_u32 v165, v165, v168, s92
	v_lshl_add_u64 v[168:169], v[166:167], 0, v[0:1]
	flat_store_short_d16_hi v[168:169], v165
	v_mul_f32_e32 v165, v80, v164
	v_bfe_u32 v168, v165, 16, 1
	v_add3_u32 v165, v165, v168, s92
	v_lshl_add_u64 v[168:169], v[166:167], 0, v[136:137]
	flat_store_short_d16_hi v[168:169], v165
	v_mul_f32_e32 v165, v81, v164
	v_bfe_u32 v168, v165, 16, 1
	v_add3_u32 v165, v165, v168, s92
	v_lshl_add_u64 v[168:169], v[166:167], 0, v[138:139]
	flat_store_short_d16_hi v[168:169], v165
	v_mul_f32_e32 v165, v74, v164
	v_bfe_u32 v168, v165, 16, 1
	v_add3_u32 v165, v165, v168, s92
	v_lshl_add_u64 v[168:169], v[166:167], 0, v[140:141]
	flat_store_short_d16_hi v[168:169], v165
	v_mul_f32_e32 v165, v75, v164
	v_bfe_u32 v168, v165, 16, 1
	v_add3_u32 v165, v165, v168, s92
	v_lshl_add_u64 v[168:169], v[166:167], 0, v[142:143]
	flat_store_short_d16_hi v[168:169], v165
	v_mul_f32_e32 v165, v76, v164
	v_bfe_u32 v168, v165, 16, 1
	v_add3_u32 v165, v165, v168, s92
	v_lshl_add_u64 v[168:169], v[166:167], 0, v[144:145]
	flat_store_short_d16_hi v[168:169], v165
	v_mul_f32_e32 v165, v77, v164
	v_bfe_u32 v168, v165, 16, 1
	v_add3_u32 v165, v165, v168, s92
	v_lshl_add_u64 v[168:169], v[166:167], 0, v[146:147]
	flat_store_short_d16_hi v[168:169], v165
	v_mul_f32_e32 v165, v70, v164
	v_bfe_u32 v168, v165, 16, 1
	v_add3_u32 v165, v165, v168, s92
	v_lshl_add_u64 v[168:169], v[166:167], 0, v[148:149]
	flat_store_short_d16_hi v[168:169], v165
	v_mul_f32_e32 v165, v71, v164
	v_bfe_u32 v168, v165, 16, 1
	v_add3_u32 v165, v165, v168, s92
	v_lshl_add_u64 v[168:169], v[166:167], 0, v[150:151]
	flat_store_short_d16_hi v[168:169], v165
	v_mul_f32_e32 v165, v72, v164
	v_bfe_u32 v168, v165, 16, 1
	v_add3_u32 v165, v165, v168, s92
	v_lshl_add_u64 v[168:169], v[166:167], 0, v[152:153]
	flat_store_short_d16_hi v[168:169], v165
	v_mul_f32_e32 v165, v73, v164
	v_bfe_u32 v168, v165, 16, 1
	v_add3_u32 v165, v165, v168, s92
	v_lshl_add_u64 v[168:169], v[166:167], 0, v[154:155]
	flat_store_short_d16_hi v[168:169], v165
	v_mul_f32_e32 v165, v66, v164
	v_bfe_u32 v168, v165, 16, 1
	v_add3_u32 v165, v165, v168, s92
	v_lshl_add_u64 v[168:169], v[166:167], 0, v[156:157]
	flat_store_short_d16_hi v[168:169], v165
	v_mul_f32_e32 v165, v67, v164
	v_bfe_u32 v168, v165, 16, 1
	v_add3_u32 v165, v165, v168, s92
	v_lshl_add_u64 v[168:169], v[166:167], 0, v[158:159]
	flat_store_short_d16_hi v[168:169], v165
	v_mul_f32_e32 v165, v68, v164
	v_bfe_u32 v168, v165, 16, 1
	v_add3_u32 v165, v165, v168, s92
	v_lshl_add_u64 v[168:169], v[166:167], 0, v[160:161]
	v_mul_f32_e32 v164, v69, v164
	flat_store_short_d16_hi v[168:169], v165
	v_bfe_u32 v165, v164, 16, 1
	v_add3_u32 v168, v164, v165, s92
	v_lshl_add_u64 v[164:165], v[166:167], 0, v[162:163]
	flat_store_short_d16_hi v[164:165], v168
	v_mov_b32_e32 v164, 1.0
	s_and_b64 vcc, exec, s[44:45]
	v_mov_b32_e32 v165, 1.0
	s_cbranch_vccnz .LBB0_463
	v_lshl_add_u64 v[166:167], v[130:131], 2, s[74:75]
	flat_load_dword v165, v[166:167] offset:512
	s_waitcnt vmcnt(0) lgkmcnt(0)
	v_fmamk_f32 v165, v165, 0x3a000000, v229
	v_mul_f32_e32 v166, 0x4b800000, v165
	v_cmp_gt_f32_e32 vcc, s33, v165
	s_nop 1
	v_cndmask_b32_e32 v165, v165, v166, vcc
	v_rsq_f32_e32 v165, v165
	s_nop 0
	v_mul_f32_e32 v166, 0x45800000, v165
	v_cndmask_b32_e32 v165, v165, v166, vcc
.LBB0_463:
	v_mul_f32_e32 v168, v62, v165
	v_bfe_u32 v169, v168, 16, 1
	v_add3_u32 v168, v168, v169, s92
	s_mov_b64 s[12:13], 0x100
	flat_store_short_d16_hi v[134:135], v168 offset:256
	v_mul_f32_e32 v168, v63, v165
	v_lshl_add_u64 v[166:167], v[132:133], 0, s[12:13]
	v_bfe_u32 v169, v168, 16, 1
	v_add3_u32 v170, v168, v169, s92
	v_lshl_add_u64 v[168:169], v[166:167], 0, v[0:1]
	flat_store_short_d16_hi v[168:169], v170
	v_mul_f32_e32 v168, v64, v165
	v_bfe_u32 v169, v168, 16, 1
	v_add3_u32 v170, v168, v169, s92
	v_lshl_add_u64 v[168:169], v[166:167], 0, v[136:137]
	flat_store_short_d16_hi v[168:169], v170
	v_mul_f32_e32 v168, v65, v165
	v_bfe_u32 v169, v168, 16, 1
	v_add3_u32 v170, v168, v169, s92
	v_lshl_add_u64 v[168:169], v[166:167], 0, v[138:139]
	flat_store_short_d16_hi v[168:169], v170
	v_mul_f32_e32 v168, v58, v165
	v_bfe_u32 v169, v168, 16, 1
	v_add3_u32 v170, v168, v169, s92
	v_lshl_add_u64 v[168:169], v[166:167], 0, v[140:141]
	flat_store_short_d16_hi v[168:169], v170
	v_mul_f32_e32 v168, v59, v165
	v_bfe_u32 v169, v168, 16, 1
	v_add3_u32 v170, v168, v169, s92
	v_lshl_add_u64 v[168:169], v[166:167], 0, v[142:143]
	flat_store_short_d16_hi v[168:169], v170
	v_mul_f32_e32 v168, v60, v165
	v_bfe_u32 v169, v168, 16, 1
	v_add3_u32 v170, v168, v169, s92
	v_lshl_add_u64 v[168:169], v[166:167], 0, v[144:145]
	flat_store_short_d16_hi v[168:169], v170
	v_mul_f32_e32 v168, v61, v165
	v_bfe_u32 v169, v168, 16, 1
	v_add3_u32 v170, v168, v169, s92
	v_lshl_add_u64 v[168:169], v[166:167], 0, v[146:147]
	flat_store_short_d16_hi v[168:169], v170
	v_mul_f32_e32 v168, v54, v165
	v_bfe_u32 v169, v168, 16, 1
	v_add3_u32 v170, v168, v169, s92
; DI unsigned f2bf(float f) { unsigned u = __builtin_bit_cast(unsigned, f); return (u + 0x7fffu + ((u >> 16) & 1u)) >> 16; }
;     DI void operator()(const f32x4 (&acc)[2][2][4][2], const Unit& u, int wr, int wc, int fr, int fq) const {
;     ...
;                 bf16_t* base = ((u.pm * BM) >> 13) ? VTS1 : VTS0; const int ldt = SEQ, rowi = ((u.pm * BM) & (SEQ - 1)) + wr * 64 + fr, col0 = (u.pn - vt_lo) * BM + wc * 32 + 8 * fq;
; #pragma unroll
;                 for (int ai = 0; ai < 2; ++ai)
; #pragma unroll
;                     for (int m = 0; m < 4; ++m) { const int row = rowi + ai * HALF + m * 16;
;                         const float rs_ = ss_in ? rsqrtf(ss_in[row0 + ai * HALF + m * 16] * (1.f / DM) + EPS) : 1.f;
; #pragma unroll
;                         for (int bj = 0; bj < 2; ++bj)
; #pragma unroll
;                             for (int n = 0; n < 2; ++n)
; #pragma unroll
;                                 for (int j = 0; j < 4; ++j) base[(size_t)(col0 + bj * HALF + 4 * n + j) * ldt + row] = (bf16_t)f2bf(acc[ai][bj][m][n][j] * rs_); }
	v_lshl_add_u64 v[168:169], v[166:167], 0, v[148:149]
	flat_store_short_d16_hi v[168:169], v170
	v_mul_f32_e32 v168, v55, v165
	v_bfe_u32 v169, v168, 16, 1
	v_add3_u32 v170, v168, v169, s92
	v_lshl_add_u64 v[168:169], v[166:167], 0, v[150:151]
	flat_store_short_d16_hi v[168:169], v170
	v_mul_f32_e32 v168, v56, v165
	v_bfe_u32 v169, v168, 16, 1
	v_add3_u32 v170, v168, v169, s92
	v_lshl_add_u64 v[168:169], v[166:167], 0, v[152:153]
	flat_store_short_d16_hi v[168:169], v170
	v_mul_f32_e32 v168, v57, v165
	v_bfe_u32 v169, v168, 16, 1
	v_add3_u32 v170, v168, v169, s92
	v_lshl_add_u64 v[168:169], v[166:167], 0, v[154:155]
	flat_store_short_d16_hi v[168:169], v170
	v_mul_f32_e32 v168, v50, v165
	v_bfe_u32 v169, v168, 16, 1
	v_add3_u32 v170, v168, v169, s92
	v_lshl_add_u64 v[168:169], v[166:167], 0, v[156:157]
	flat_store_short_d16_hi v[168:169], v170
	v_mul_f32_e32 v168, v51, v165
	v_bfe_u32 v169, v168, 16, 1
	v_add3_u32 v170, v168, v169, s92
	v_lshl_add_u64 v[168:169], v[166:167], 0, v[158:159]
	flat_store_short_d16_hi v[168:169], v170
	v_mul_f32_e32 v168, v52, v165
	v_bfe_u32 v169, v168, 16, 1
	v_add3_u32 v170, v168, v169, s92
	v_lshl_add_u64 v[168:169], v[166:167], 0, v[160:161]
	v_mul_f32_e32 v165, v53, v165
	flat_store_short_d16_hi v[168:169], v170
	v_bfe_u32 v168, v165, 16, 1
	v_add3_u32 v165, v165, v168, s92
	v_lshl_add_u64 v[166:167], v[166:167], 0, v[162:163]
	s_and_b64 vcc, exec, s[44:45]
	flat_store_short_d16_hi v[166:167], v165
	s_cbranch_vccnz .LBB0_465
	v_lshl_add_u64 v[164:165], v[130:131], 2, s[74:75]
	flat_load_dword v164, v[164:165] offset:576
	s_waitcnt vmcnt(0) lgkmcnt(0)
	v_fmamk_f32 v164, v164, 0x3a000000, v229
	v_mul_f32_e32 v165, 0x4b800000, v164
	v_cmp_gt_f32_e32 vcc, s33, v164
	s_nop 1
	v_cndmask_b32_e32 v164, v164, v165, vcc
	v_rsq_f32_e32 v164, v164
	s_nop 0
	v_mul_f32_e32 v165, 0x45800000, v164
	v_cndmask_b32_e32 v164, v164, v165, vcc
.LBB0_465:
	v_mul_f32_e32 v165, v46, v164
	v_bfe_u32 v168, v165, 16, 1
	v_add3_u32 v165, v165, v168, s92
	s_mov_b64 s[12:13], 0x120
	flat_store_short_d16_hi v[134:135], v165 offset:288
	v_mul_f32_e32 v165, v47, v164
	v_lshl_add_u64 v[166:167], v[132:133], 0, s[12:13]
	v_bfe_u32 v168, v165, 16, 1
	v_add3_u32 v165, v165, v168, s92
	v_lshl_add_u64 v[168:169], v[166:167], 0, v[0:1]
	flat_store_short_d16_hi v[168:169], v165
	v_mul_f32_e32 v165, v48, v164
	v_bfe_u32 v168, v165, 16, 1
	v_add3_u32 v165, v165, v168, s92
	v_lshl_add_u64 v[168:169], v[166:167], 0, v[136:137]
	flat_store_short_d16_hi v[168:169], v165
	v_mul_f32_e32 v165, v49, v164
	v_bfe_u32 v168, v165, 16, 1
	v_add3_u32 v165, v165, v168, s92
	v_lshl_add_u64 v[168:169], v[166:167], 0, v[138:139]
	flat_store_short_d16_hi v[168:169], v165
	v_mul_f32_e32 v165, v42, v164
	v_bfe_u32 v168, v165, 16, 1
	v_add3_u32 v165, v165, v168, s92
	v_lshl_add_u64 v[168:169], v[166:167], 0, v[140:141]
	flat_store_short_d16_hi v[168:169], v165
	v_mul_f32_e32 v165, v43, v164
	v_bfe_u32 v168, v165, 16, 1
	v_add3_u32 v165, v165, v168, s92
	v_lshl_add_u64 v[168:169], v[166:167], 0, v[142:143]
	flat_store_short_d16_hi v[168:169], v165
	v_mul_f32_e32 v165, v44, v164
	v_bfe_u32 v168, v165, 16, 1
	v_add3_u32 v165, v165, v168, s92
	v_lshl_add_u64 v[168:169], v[166:167], 0, v[144:145]
	flat_store_short_d16_hi v[168:169], v165
	v_mul_f32_e32 v165, v45, v164
	v_bfe_u32 v168, v165, 16, 1
	v_add3_u32 v165, v165, v168, s92
	v_lshl_add_u64 v[168:169], v[166:167], 0, v[146:147]
	flat_store_short_d16_hi v[168:169], v165
	v_mul_f32_e32 v165, v38, v164
	v_bfe_u32 v168, v165, 16, 1
	v_add3_u32 v165, v165, v168, s92
	v_lshl_add_u64 v[168:169], v[166:167], 0, v[148:149]
	flat_store_short_d16_hi v[168:169], v165
	v_mul_f32_e32 v165, v39, v164
	v_bfe_u32 v168, v165, 16, 1
	v_add3_u32 v165, v165, v168, s92
	v_lshl_add_u64 v[168:169], v[166:167], 0, v[150:151]
	flat_store_short_d16_hi v[168:169], v165
	v_mul_f32_e32 v165, v40, v164
	v_bfe_u32 v168, v165, 16, 1
	v_add3_u32 v165, v165, v168, s92
	v_lshl_add_u64 v[168:169], v[166:167], 0, v[152:153]
	flat_store_short_d16_hi v[168:169], v165
	v_mul_f32_e32 v165, v41, v164
	v_bfe_u32 v168, v165, 16, 1
	v_add3_u32 v165, v165, v168, s92
	v_lshl_add_u64 v[168:169], v[166:167], 0, v[154:155]
	flat_store_short_d16_hi v[168:169], v165
	v_mul_f32_e32 v165, v34, v164
	v_bfe_u32 v168, v165, 16, 1
	v_add3_u32 v165, v165, v168, s92
	v_lshl_add_u64 v[168:169], v[166:167], 0, v[156:157]
	flat_store_short_d16_hi v[168:169], v165
	v_mul_f32_e32 v165, v35, v164
	v_bfe_u32 v168, v165, 16, 1
	v_add3_u32 v165, v165, v168, s92
	v_lshl_add_u64 v[168:169], v[166:167], 0, v[158:159]
	flat_store_short_d16_hi v[168:169], v165
	v_mul_f32_e32 v165, v36, v164
	v_bfe_u32 v168, v165, 16, 1
	v_add3_u32 v165, v165, v168, s92
	v_lshl_add_u64 v[168:169], v[166:167], 0, v[160:161]
	v_mul_f32_e32 v164, v37, v164
	flat_store_short_d16_hi v[168:169], v165
	v_bfe_u32 v165, v164, 16, 1
	v_add3_u32 v168, v164, v165, s92
	v_lshl_add_u64 v[164:165], v[166:167], 0, v[162:163]
	flat_store_short_d16_hi v[164:165], v168
	v_mov_b32_e32 v164, 1.0
	s_and_b64 vcc, exec, s[44:45]
	v_mov_b32_e32 v165, 1.0
	s_cbranch_vccnz .LBB0_467
	v_lshl_add_u64 v[166:167], v[130:131], 2, s[74:75]
	flat_load_dword v165, v[166:167] offset:640
	s_waitcnt vmcnt(0) lgkmcnt(0)
	v_fmamk_f32 v165, v165, 0x3a000000, v229
	v_mul_f32_e32 v166, 0x4b800000, v165
	v_cmp_gt_f32_e32 vcc, s33, v165
	s_nop 1
	v_cndmask_b32_e32 v165, v165, v166, vcc
	v_rsq_f32_e32 v165, v165
	s_nop 0
	v_mul_f32_e32 v166, 0x45800000, v165
	v_cndmask_b32_e32 v165, v165, v166, vcc
; DI unsigned f2bf(float f) { unsigned u = __builtin_bit_cast(unsigned, f); return (u + 0x7fffu + ((u >> 16) & 1u)) >> 16; }
;     DI void operator()(const f32x4 (&acc)[2][2][4][2], const Unit& u, int wr, int wc, int fr, int fq) const {
;     ...
;                 bf16_t* base = ((u.pm * BM) >> 13) ? VTS1 : VTS0; const int ldt = SEQ, rowi = ((u.pm * BM) & (SEQ - 1)) + wr * 64 + fr, col0 = (u.pn - vt_lo) * BM + wc * 32 + 8 * fq;
; #pragma unroll
;                 for (int ai = 0; ai < 2; ++ai)
; #pragma unroll
;                     for (int m = 0; m < 4; ++m) { const int row = rowi + ai * HALF + m * 16;
;                         const float rs_ = ss_in ? rsqrtf(ss_in[row0 + ai * HALF + m * 16] * (1.f / DM) + EPS) : 1.f;
; #pragma unroll
;                         for (int bj = 0; bj < 2; ++bj)
; #pragma unroll
;                             for (int n = 0; n < 2; ++n)
; #pragma unroll
;                                 for (int j = 0; j < 4; ++j) base[(size_t)(col0 + bj * HALF + 4 * n + j) * ldt + row] = (bf16_t)f2bf(acc[ai][bj][m][n][j] * rs_); }
.LBB0_467:
	v_mul_f32_e32 v168, v30, v165
	v_bfe_u32 v169, v168, 16, 1
	v_add3_u32 v168, v168, v169, s92
	s_mov_b64 s[12:13], 0x140
	flat_store_short_d16_hi v[134:135], v168 offset:320
	v_mul_f32_e32 v168, v31, v165
	v_lshl_add_u64 v[166:167], v[132:133], 0, s[12:13]
	v_bfe_u32 v169, v168, 16, 1
	v_add3_u32 v170, v168, v169, s92
	v_lshl_add_u64 v[168:169], v[166:167], 0, v[0:1]
	flat_store_short_d16_hi v[168:169], v170
	v_mul_f32_e32 v168, v32, v165
	v_bfe_u32 v169, v168, 16, 1
	v_add3_u32 v170, v168, v169, s92
	v_lshl_add_u64 v[168:169], v[166:167], 0, v[136:137]
	flat_store_short_d16_hi v[168:169], v170
	v_mul_f32_e32 v168, v33, v165
	v_bfe_u32 v169, v168, 16, 1
	v_add3_u32 v170, v168, v169, s92
	v_lshl_add_u64 v[168:169], v[166:167], 0, v[138:139]
	flat_store_short_d16_hi v[168:169], v170
	v_mul_f32_e32 v168, v26, v165
	v_bfe_u32 v169, v168, 16, 1
	v_add3_u32 v170, v168, v169, s92
	v_lshl_add_u64 v[168:169], v[166:167], 0, v[140:141]
	flat_store_short_d16_hi v[168:169], v170
	v_mul_f32_e32 v168, v27, v165
	v_bfe_u32 v169, v168, 16, 1
	v_add3_u32 v170, v168, v169, s92
	v_lshl_add_u64 v[168:169], v[166:167], 0, v[142:143]
	flat_store_short_d16_hi v[168:169], v170
	v_mul_f32_e32 v168, v28, v165
	v_bfe_u32 v169, v168, 16, 1
	v_add3_u32 v170, v168, v169, s92
	v_lshl_add_u64 v[168:169], v[166:167], 0, v[144:145]
	flat_store_short_d16_hi v[168:169], v170
	v_mul_f32_e32 v168, v29, v165
	v_bfe_u32 v169, v168, 16, 1
	v_add3_u32 v170, v168, v169, s92
	v_lshl_add_u64 v[168:169], v[166:167], 0, v[146:147]
	flat_store_short_d16_hi v[168:169], v170
	v_mul_f32_e32 v168, v22, v165
	v_bfe_u32 v169, v168, 16, 1
	v_add3_u32 v170, v168, v169, s92
	v_lshl_add_u64 v[168:169], v[166:167], 0, v[148:149]
	flat_store_short_d16_hi v[168:169], v170
	v_mul_f32_e32 v168, v23, v165
	v_bfe_u32 v169, v168, 16, 1
	v_add3_u32 v170, v168, v169, s92
	v_lshl_add_u64 v[168:169], v[166:167], 0, v[150:151]
	flat_store_short_d16_hi v[168:169], v170
	v_mul_f32_e32 v168, v24, v165
	v_bfe_u32 v169, v168, 16, 1
	v_add3_u32 v170, v168, v169, s92
	v_lshl_add_u64 v[168:169], v[166:167], 0, v[152:153]
	flat_store_short_d16_hi v[168:169], v170
	v_mul_f32_e32 v168, v25, v165
	v_bfe_u32 v169, v168, 16, 1
	v_add3_u32 v170, v168, v169, s92
	v_lshl_add_u64 v[168:169], v[166:167], 0, v[154:155]
	flat_store_short_d16_hi v[168:169], v170
	v_mul_f32_e32 v168, v18, v165
	v_bfe_u32 v169, v168, 16, 1
	v_add3_u32 v170, v168, v169, s92
	v_lshl_add_u64 v[168:169], v[166:167], 0, v[156:157]
	flat_store_short_d16_hi v[168:169], v170
	v_mul_f32_e32 v168, v19, v165
	v_bfe_u32 v169, v168, 16, 1
	v_add3_u32 v170, v168, v169, s92
	v_lshl_add_u64 v[168:169], v[166:167], 0, v[158:159]
	flat_store_short_d16_hi v[168:169], v170
	v_mul_f32_e32 v168, v20, v165
	v_bfe_u32 v169, v168, 16, 1
	v_add3_u32 v170, v168, v169, s92
	v_lshl_add_u64 v[168:169], v[166:167], 0, v[160:161]
	v_mul_f32_e32 v165, v21, v165
	flat_store_short_d16_hi v[168:169], v170
	v_bfe_u32 v168, v165, 16, 1
	v_add3_u32 v165, v165, v168, s92
	v_lshl_add_u64 v[166:167], v[166:167], 0, v[162:163]
	s_and_b64 vcc, exec, s[44:45]
	flat_store_short_d16_hi v[166:167], v165
	s_cbranch_vccnz .LBB0_469
	v_lshl_add_u64 v[130:131], v[130:131], 2, s[74:75]
	flat_load_dword v130, v[130:131] offset:704
	s_waitcnt vmcnt(0) lgkmcnt(0)
	v_fmamk_f32 v130, v130, 0x3a000000, v229
	v_mul_f32_e32 v131, 0x4b800000, v130
	v_cmp_gt_f32_e32 vcc, s33, v130
	s_nop 1
	v_cndmask_b32_e32 v130, v130, v131, vcc
	v_rsq_f32_e32 v130, v130
	s_nop 0
	v_mul_f32_e32 v131, 0x45800000, v130
	v_cndmask_b32_e32 v164, v130, v131, vcc
